# P7 GEMM epilogue: bf16 residual loads of row groups 1-3 hoisted to epilogue top (fresh VGPRs), counted vmcnt waits
# baseline (speedup 1.0000x reference)
; __device__ __forceinline__ unsigned cvtpk(float lo, float hi) { f32x2 v = {lo, hi}; bf16x2_t b = __builtin_convertvector(v, bf16x2_t); return __builtin_bit_cast(unsigned, b); }
;     __device__ __forceinline__ void operator()(const f32x4 (&acc)[2][2][4][2], const Unit& u, int wr, int wc, int fr, int fq) const {
;     ...
;                 u32x4 rb[2][2];
; #pragma unroll
;                 for (int mm = 0; mm < 2; ++mm) {
;                     const int row = u.pm * BM + ai * HALF + wr * 64 + (2 * mp + mm) * 16 + fr;
; #pragma unroll
;                     for (int bj = 0; bj < 2; ++bj) rb[mm][bj] = *(const u32x4*)(res_b + (size_t)row * D + u.pn * BM + bj * HALF + wc * 32 + 8 * fq);
;                 }
;                 __builtin_amdgcn_sched_barrier(0);
; #pragma unroll
;                 for (int mm = 0; mm < 2; ++mm)
; #pragma unroll
;                     for (int bj = 0; bj < 2; ++bj) { const u32x4 w = rb[mm][bj];
;                         rv[mm][bj][0] = (f32x4){bflo(w.x), bfhi(w.x), bflo(w.y), bfhi(w.y)}; rv[mm][bj][1] = (f32x4){bflo(w.z), bfhi(w.z), bflo(w.w), bfhi(w.w)}; }
;             }
;             __builtin_amdgcn_sched_barrier(0);
; #pragma unroll
;             for (int mm = 0; mm < 2; ++mm) {
;                 const int m = 2 * mp + mm;
;                 const int row = u.pm * BM + ai * HALF + wr * 64 + m * 16 + fr;
;                 float q = 0.f;
; #pragma unroll
;                 for (int bj = 0; bj < 2; ++bj) {
;                     const int col = u.pn * BM + bj * HALF + wc * 32 + 8 * fq;
;                     const f32x4 a = acc[ai][bj][m][0] + rv[mm][bj][0], b = acc[ai][bj][m][1] + rv[mm][bj][1];
;                     if (out) { __builtin_nontemporal_store(a, (f32x4*)(out + (size_t)row * D + col)); __builtin_nontemporal_store(b, (f32x4*)(out + (size_t)row * D + col + 4)); }
;                     if (outb) {
;                         u32x4 w; w.x = cvtpk(a[0], a[1]); w.y = cvtpk(a[2], a[3]); w.z = cvtpk(b[0], b[1]); w.w = cvtpk(b[2], b[3]);
;                         *(u32x4*)(outb + (size_t)row * D + col) = w;
.LBB0_1370:
	v_lshl_add_u32 v154, s45, 8, v180
	s_lshl_b32 s8, s44, 8
	s_ashr_i32 s9, s8, 31
	v_ashrrev_i32_e32 v155, 31, v154
	v_or_b32_e32 v174, 16, v154
	v_lshl_add_u64 v[158:159], s[8:9], 1, v[148:149]
	v_lshlrev_b64 v[176:177], 11, v[154:155]
	v_ashrrev_i32_e32 v175, 31, v174
	v_lshl_add_u64 v[130:131], v[158:159], 0, v[176:177]
	v_lshlrev_b64 v[160:161], 11, v[174:175]
	global_load_dwordx4 v[184:187], v[130:131], off
	global_load_dwordx4 v[138:141], v[130:131], off offset:256
	v_lshl_add_u64 v[130:131], v[158:159], 0, v[160:161]
	global_load_dwordx4 v[134:137], v[130:131], off
	s_nop 0
	global_load_dwordx4 v[130:133], v[130:131], off offset:256
	v_lshl_add_u64 v[244:245], v[158:159], 0, v[176:177]
	s_mov_b32 s101, 0
	s_mov_b32 s100, 0x10000
	v_lshl_add_u64 v[250:251], v[244:245], 0, s[100:101]
	global_load_dwordx4 v[192:195], v[250:251], off
	global_load_dwordx4 v[196:199], v[250:251], off offset:256
	s_mov_b32 s100, 0x18000
	v_lshl_add_u64 v[250:251], v[244:245], 0, s[100:101]
	global_load_dwordx4 v[208:211], v[250:251], off
	global_load_dwordx4 v[212:215], v[250:251], off offset:256
	s_mov_b32 s100, 0x40000
	v_lshl_add_u64 v[250:251], v[244:245], 0, s[100:101]
	global_load_dwordx4 v[216:219], v[250:251], off
	global_load_dwordx4 v[220:223], v[250:251], off offset:256
	s_mov_b32 s100, 0x48000
	v_lshl_add_u64 v[250:251], v[244:245], 0, s[100:101]
	global_load_dwordx4 v[224:227], v[250:251], off
	global_load_dwordx4 v[228:231], v[250:251], off offset:256
	s_mov_b32 s100, 0x50000
	v_lshl_add_u64 v[250:251], v[244:245], 0, s[100:101]
	global_load_dwordx4 v[232:235], v[250:251], off
	global_load_dwordx4 v[236:239], v[250:251], off offset:256
	s_mov_b32 s100, 0x58000
	v_lshl_add_u64 v[250:251], v[244:245], 0, s[100:101]
	global_load_dwordx4 v[240:243], v[250:251], off
	global_load_dwordx4 v[252:255], v[250:251], off offset:256
	v_or_b32_e32 v156, s8, v182
	s_waitcnt vmcnt(12)
	v_lshlrev_b32_e32 v178, 16, v184
	v_and_b32_e32 v179, 0xffff0000, v184
	v_lshlrev_b32_e32 v184, 16, v185
	v_and_b32_e32 v185, 0xffff0000, v185
	v_lshlrev_b32_e32 v188, 16, v186
	v_and_b32_e32 v189, 0xffff0000, v186
	v_lshlrev_b32_e32 v186, 16, v187
	v_and_b32_e32 v187, 0xffff0000, v187
	v_lshlrev_b64 v[190:191], 10, v[154:155]
	v_cndmask_b32_e64 v157, 0, 1, s[20:21]
	v_pk_add_f32 v[128:129], v[128:129], v[184:185]
	v_pk_add_f32 v[126:127], v[126:127], v[178:179]
	v_pk_add_f32 v[124:125], v[124:125], v[186:187]
	v_pk_add_f32 v[122:123], v[122:123], v[188:189]
	v_cmp_ne_u32_e64 s[8:9], 1, v157
	s_andn2_b64 vcc, exec, s[20:21]
	v_ashrrev_i32_e32 v157, 31, v156
	v_lshl_add_u64 v[178:179], v[190:191], 2, s[14:15]
	s_cbranch_vccnz .LBB0_1372
	v_lshl_add_u64 v[184:185], v[156:157], 2, v[178:179]
	global_store_dwordx4 v[184:185], v[126:129], off nt
	global_store_dwordx4 v[184:185], v[122:125], off offset:16 nt

;     __device__ __forceinline__ void operator()(const f32x4 (&acc)[2][2][4][2], const Unit& u, int wr, int wc, int fr, int fq) const {
;     ...
;                     for (int bj = 0; bj < 2; ++bj) { const u32x4 w = rb[mm][bj];
;                         rv[mm][bj][0] = (f32x4){bflo(w.x), bfhi(w.x), bflo(w.y), bfhi(w.y)}; rv[mm][bj][1] = (f32x4){bflo(w.z), bfhi(w.z), bflo(w.w), bfhi(w.w)}; }
;             }
;             __builtin_amdgcn_sched_barrier(0);
; #pragma unroll
;             for (int mm = 0; mm < 2; ++mm) {
;                 const int m = 2 * mp + mm;
;                 const int row = u.pm * BM + ai * HALF + wr * 64 + m * 16 + fr;
;                 float q = 0.f;
; #pragma unroll
;                 for (int bj = 0; bj < 2; ++bj) {
;                     const int col = u.pn * BM + bj * HALF + wc * 32 + 8 * fq;
;                     const f32x4 a = acc[ai][bj][m][0] + rv[mm][bj][0], b = acc[ai][bj][m][1] + rv[mm][bj][1];
;                     if (out) { __builtin_nontemporal_store(a, (f32x4*)(out + (size_t)row * D + col)); __builtin_nontemporal_store(b, (f32x4*)(out + (size_t)row * D + col + 4)); }
.LBB0_1390:
	v_or_b32_e32 v120, 32, v154
	v_ashrrev_i32_e32 v121, 31, v120
	v_or_b32_e32 v112, 48, v154
	v_lshlrev_b64 v[114:115], 11, v[120:121]
	v_ashrrev_i32_e32 v113, 31, v112
	v_lshl_add_u64 v[98:99], v[158:159], 0, v[114:115]
	v_lshlrev_b64 v[110:111], 11, v[112:113]
	v_lshl_add_u64 v[98:99], v[158:159], 0, v[110:111]
	s_waitcnt lgkmcnt(0)
	s_nop 0
	s_waitcnt vmcnt(15)
	v_lshlrev_b32_e32 v122, 16, v192
	v_and_b32_e32 v123, 0xffff0000, v192
	v_lshlrev_b32_e32 v116, 16, v193
	v_and_b32_e32 v117, 0xffff0000, v193
	v_lshlrev_b32_e32 v124, 16, v194
	v_and_b32_e32 v125, 0xffff0000, v194
	v_lshlrev_b32_e32 v118, 16, v195
	v_and_b32_e32 v119, 0xffff0000, v195
	v_lshlrev_b64 v[120:121], 10, v[120:121]
	v_pk_add_f32 v[96:97], v[96:97], v[116:117]
	v_pk_add_f32 v[94:95], v[94:95], v[122:123]
	v_pk_add_f32 v[92:93], v[92:93], v[118:119]
	v_pk_add_f32 v[90:91], v[90:91], v[124:125]
	s_and_b64 vcc, exec, s[8:9]
	v_lshl_add_u64 v[116:117], v[120:121], 2, s[14:15]
	s_cbranch_vccnz .LBB0_1392
	v_lshl_add_u64 v[118:119], v[156:157], 2, v[116:117]
	global_store_dwordx4 v[118:119], v[94:97], off nt
	global_store_dwordx4 v[118:119], v[90:93], off offset:16 nt

;     __device__ __forceinline__ void operator()(const f32x4 (&acc)[2][2][4][2], const Unit& u, int wr, int wc, int fr, int fq) const {
;     ...
;                     for (int bj = 0; bj < 2; ++bj) { const u32x4 w = rb[mm][bj];
;                         rv[mm][bj][0] = (f32x4){bflo(w.x), bfhi(w.x), bflo(w.y), bfhi(w.y)}; rv[mm][bj][1] = (f32x4){bflo(w.z), bfhi(w.z), bflo(w.w), bfhi(w.w)}; }
;             }
;             __builtin_amdgcn_sched_barrier(0);
; #pragma unroll
;             for (int mm = 0; mm < 2; ++mm) {
;                 const int m = 2 * mp + mm;
;                 const int row = u.pm * BM + ai * HALF + wr * 64 + m * 16 + fr;
;                 float q = 0.f;
; #pragma unroll
;                 for (int bj = 0; bj < 2; ++bj) {
;                     const int col = u.pn * BM + bj * HALF + wc * 32 + 8 * fq;
;                     const f32x4 a = acc[ai][bj][m][0] + rv[mm][bj][0], b = acc[ai][bj][m][1] + rv[mm][bj][1];
;                     if (out) { __builtin_nontemporal_store(a, (f32x4*)(out + (size_t)row * D + col)); __builtin_nontemporal_store(b, (f32x4*)(out + (size_t)row * D + col + 4)); }
.LBB0_1394:
	s_waitcnt vmcnt(15)
	v_lshlrev_b32_e32 v90, 16, v196
	v_and_b32_e32 v91, 0xffff0000, v196
	v_lshlrev_b32_e32 v92, 16, v197
	v_and_b32_e32 v93, 0xffff0000, v197
	v_lshlrev_b32_e32 v94, 16, v198
	v_and_b32_e32 v95, 0xffff0000, v198
	v_lshlrev_b32_e32 v96, 16, v199
	v_and_b32_e32 v97, 0xffff0000, v199
	v_pk_add_f32 v[88:89], v[88:89], v[92:93]
	v_pk_add_f32 v[86:87], v[86:87], v[90:91]
	v_pk_add_f32 v[84:85], v[84:85], v[96:97]
	s_and_b64 vcc, exec, s[8:9]
	v_pk_add_f32 v[82:83], v[82:83], v[94:95]
	s_cbranch_vccnz .LBB0_1396
	v_lshl_add_u64 v[90:91], v[156:157], 2, v[116:117]
	global_store_dwordx4 v[90:91], v[86:89], off offset:512 nt
	global_store_dwordx4 v[90:91], v[82:85], off offset:528 nt

;     __device__ __forceinline__ void operator()(const f32x4 (&acc)[2][2][4][2], const Unit& u, int wr, int wc, int fr, int fq) const {
;     ...
;                     for (int bj = 0; bj < 2; ++bj) { const u32x4 w = rb[mm][bj];
;                         rv[mm][bj][0] = (f32x4){bflo(w.x), bfhi(w.x), bflo(w.y), bfhi(w.y)}; rv[mm][bj][1] = (f32x4){bflo(w.z), bfhi(w.z), bflo(w.w), bfhi(w.w)}; }
;             }
;             __builtin_amdgcn_sched_barrier(0);
; #pragma unroll
;             for (int mm = 0; mm < 2; ++mm) {
;                 const int m = 2 * mp + mm;
;                 const int row = u.pm * BM + ai * HALF + wr * 64 + m * 16 + fr;
;                 float q = 0.f;
; #pragma unroll
;                 for (int bj = 0; bj < 2; ++bj) {
;                     const int col = u.pn * BM + bj * HALF + wc * 32 + 8 * fq;
;                     const f32x4 a = acc[ai][bj][m][0] + rv[mm][bj][0], b = acc[ai][bj][m][1] + rv[mm][bj][1];
;                     if (out) { __builtin_nontemporal_store(a, (f32x4*)(out + (size_t)row * D + col)); __builtin_nontemporal_store(b, (f32x4*)(out + (size_t)row * D + col + 4)); }
.LBB0_1400:
	s_waitcnt vmcnt(15)
	v_lshlrev_b32_e32 v82, 16, v208
	v_and_b32_e32 v83, 0xffff0000, v208
	v_lshlrev_b32_e32 v84, 16, v209
	v_and_b32_e32 v85, 0xffff0000, v209
	v_lshlrev_b32_e32 v86, 16, v210
	s_waitcnt lgkmcnt(0)
	v_and_b32_e32 v87, 0xffff0000, v210
	v_lshlrev_b32_e32 v88, 16, v211
	v_and_b32_e32 v89, 0xffff0000, v211
	v_lshlrev_b64 v[90:91], 10, v[112:113]
	v_pk_add_f32 v[80:81], v[80:81], v[84:85]
	v_pk_add_f32 v[78:79], v[78:79], v[82:83]
	v_pk_add_f32 v[76:77], v[76:77], v[88:89]
	v_pk_add_f32 v[74:75], v[74:75], v[86:87]
	s_and_b64 vcc, exec, s[8:9]
	v_lshl_add_u64 v[84:85], v[90:91], 2, s[14:15]
	s_cbranch_vccnz .LBB0_1402
	v_lshl_add_u64 v[82:83], v[156:157], 2, v[84:85]
	global_store_dwordx4 v[82:83], v[78:81], off nt
	global_store_dwordx4 v[82:83], v[74:77], off offset:16 nt

;     __device__ __forceinline__ void operator()(const f32x4 (&acc)[2][2][4][2], const Unit& u, int wr, int wc, int fr, int fq) const {
;     ...
;                     for (int bj = 0; bj < 2; ++bj) { const u32x4 w = rb[mm][bj];
;                         rv[mm][bj][0] = (f32x4){bflo(w.x), bfhi(w.x), bflo(w.y), bfhi(w.y)}; rv[mm][bj][1] = (f32x4){bflo(w.z), bfhi(w.z), bflo(w.w), bfhi(w.w)}; }
;             }
;             __builtin_amdgcn_sched_barrier(0);
; #pragma unroll
;             for (int mm = 0; mm < 2; ++mm) {
;                 const int m = 2 * mp + mm;
;                 const int row = u.pm * BM + ai * HALF + wr * 64 + m * 16 + fr;
;                 float q = 0.f;
; #pragma unroll
;                 for (int bj = 0; bj < 2; ++bj) {
;                     const int col = u.pn * BM + bj * HALF + wc * 32 + 8 * fq;
;                     const f32x4 a = acc[ai][bj][m][0] + rv[mm][bj][0], b = acc[ai][bj][m][1] + rv[mm][bj][1];
;                     if (out) { __builtin_nontemporal_store(a, (f32x4*)(out + (size_t)row * D + col)); __builtin_nontemporal_store(b, (f32x4*)(out + (size_t)row * D + col + 4)); }
.LBB0_1404:
	s_waitcnt vmcnt(15)
	v_lshlrev_b32_e32 v74, 16, v212
	v_and_b32_e32 v75, 0xffff0000, v212
	v_lshlrev_b32_e32 v76, 16, v213
	v_and_b32_e32 v77, 0xffff0000, v213
	v_lshlrev_b32_e32 v78, 16, v214
	v_and_b32_e32 v79, 0xffff0000, v214
	v_lshlrev_b32_e32 v80, 16, v215
	v_and_b32_e32 v81, 0xffff0000, v215
	v_pk_add_f32 v[72:73], v[72:73], v[76:77]
	v_pk_add_f32 v[70:71], v[70:71], v[74:75]
	v_pk_add_f32 v[68:69], v[68:69], v[80:81]
	s_and_b64 vcc, exec, s[8:9]
	v_pk_add_f32 v[66:67], v[66:67], v[78:79]
	s_cbranch_vccnz .LBB0_1406
	v_lshl_add_u64 v[74:75], v[156:157], 2, v[84:85]
	global_store_dwordx4 v[74:75], v[70:73], off offset:512 nt
	global_store_dwordx4 v[74:75], v[66:69], off offset:528 nt

;     __device__ __forceinline__ void operator()(const f32x4 (&acc)[2][2][4][2], const Unit& u, int wr, int wc, int fr, int fq) const {
;     ...
;                     for (int bj = 0; bj < 2; ++bj) { const u32x4 w = rb[mm][bj];
;                         rv[mm][bj][0] = (f32x4){bflo(w.x), bfhi(w.x), bflo(w.y), bfhi(w.y)}; rv[mm][bj][1] = (f32x4){bflo(w.z), bfhi(w.z), bflo(w.w), bfhi(w.w)}; }
;             }
;             __builtin_amdgcn_sched_barrier(0);
; #pragma unroll
;             for (int mm = 0; mm < 2; ++mm) {
;                 const int m = 2 * mp + mm;
;                 const int row = u.pm * BM + ai * HALF + wr * 64 + m * 16 + fr;
;                 float q = 0.f;
; #pragma unroll
;                 for (int bj = 0; bj < 2; ++bj) {
;                     const int col = u.pn * BM + bj * HALF + wc * 32 + 8 * fq;
;                     const f32x4 a = acc[ai][bj][m][0] + rv[mm][bj][0], b = acc[ai][bj][m][1] + rv[mm][bj][1];
;                     if (out) { __builtin_nontemporal_store(a, (f32x4*)(out + (size_t)row * D + col)); __builtin_nontemporal_store(b, (f32x4*)(out + (size_t)row * D + col + 4)); }
.LBB0_1410:
	v_add_u32_e32 v88, 0x80, v154
	v_ashrrev_i32_e32 v89, 31, v88
	v_add_u32_e32 v80, 0x90, v154
	v_lshlrev_b64 v[82:83], 11, v[88:89]
	v_ashrrev_i32_e32 v81, 31, v80
	v_lshl_add_u64 v[66:67], v[158:159], 0, v[82:83]
	v_lshlrev_b64 v[78:79], 11, v[80:81]
	v_lshl_add_u64 v[66:67], v[158:159], 0, v[78:79]
	s_waitcnt lgkmcnt(0)
	s_nop 0
	s_waitcnt vmcnt(15)
	v_lshlrev_b32_e32 v90, 16, v216
	v_and_b32_e32 v91, 0xffff0000, v216
	v_lshlrev_b32_e32 v84, 16, v217
	v_and_b32_e32 v85, 0xffff0000, v217
	v_lshlrev_b32_e32 v92, 16, v218
	v_and_b32_e32 v93, 0xffff0000, v218
	v_lshlrev_b32_e32 v86, 16, v219
	v_and_b32_e32 v87, 0xffff0000, v219
	v_lshlrev_b64 v[88:89], 10, v[88:89]
	v_pk_add_f32 v[64:65], v[64:65], v[84:85]
	v_pk_add_f32 v[62:63], v[62:63], v[90:91]
	v_pk_add_f32 v[60:61], v[60:61], v[86:87]
	v_pk_add_f32 v[58:59], v[58:59], v[92:93]
	s_and_b64 vcc, exec, s[8:9]
	v_lshl_add_u64 v[84:85], v[88:89], 2, s[14:15]
	s_cbranch_vccnz .LBB0_1412
	v_lshl_add_u64 v[86:87], v[156:157], 2, v[84:85]
	global_store_dwordx4 v[86:87], v[62:65], off nt
	global_store_dwordx4 v[86:87], v[58:61], off offset:16 nt

;     __device__ __forceinline__ void operator()(const f32x4 (&acc)[2][2][4][2], const Unit& u, int wr, int wc, int fr, int fq) const {
;     ...
;                     for (int bj = 0; bj < 2; ++bj) { const u32x4 w = rb[mm][bj];
;                         rv[mm][bj][0] = (f32x4){bflo(w.x), bfhi(w.x), bflo(w.y), bfhi(w.y)}; rv[mm][bj][1] = (f32x4){bflo(w.z), bfhi(w.z), bflo(w.w), bfhi(w.w)}; }
;             }
;             __builtin_amdgcn_sched_barrier(0);
; #pragma unroll
;             for (int mm = 0; mm < 2; ++mm) {
;                 const int m = 2 * mp + mm;
;                 const int row = u.pm * BM + ai * HALF + wr * 64 + m * 16 + fr;
;                 float q = 0.f;
; #pragma unroll
;                 for (int bj = 0; bj < 2; ++bj) {
;                     const int col = u.pn * BM + bj * HALF + wc * 32 + 8 * fq;
;                     const f32x4 a = acc[ai][bj][m][0] + rv[mm][bj][0], b = acc[ai][bj][m][1] + rv[mm][bj][1];
;                     if (out) { __builtin_nontemporal_store(a, (f32x4*)(out + (size_t)row * D + col)); __builtin_nontemporal_store(b, (f32x4*)(out + (size_t)row * D + col + 4)); }
.LBB0_1414:
	s_waitcnt vmcnt(15)
	v_lshlrev_b32_e32 v58, 16, v220
	v_and_b32_e32 v59, 0xffff0000, v220
	v_lshlrev_b32_e32 v60, 16, v221
	v_and_b32_e32 v61, 0xffff0000, v221
	v_lshlrev_b32_e32 v62, 16, v222
	v_and_b32_e32 v63, 0xffff0000, v222
	v_lshlrev_b32_e32 v64, 16, v223
	v_and_b32_e32 v65, 0xffff0000, v223
	v_pk_add_f32 v[56:57], v[56:57], v[60:61]
	v_pk_add_f32 v[54:55], v[54:55], v[58:59]
	v_pk_add_f32 v[52:53], v[52:53], v[64:65]
	s_and_b64 vcc, exec, s[8:9]
	v_pk_add_f32 v[50:51], v[50:51], v[62:63]
	s_cbranch_vccnz .LBB0_1416
	v_lshl_add_u64 v[58:59], v[156:157], 2, v[84:85]
	global_store_dwordx4 v[58:59], v[54:57], off offset:512 nt
	global_store_dwordx4 v[58:59], v[50:53], off offset:528 nt

;     __device__ __forceinline__ void operator()(const f32x4 (&acc)[2][2][4][2], const Unit& u, int wr, int wc, int fr, int fq) const {
;     ...
;                     for (int bj = 0; bj < 2; ++bj) { const u32x4 w = rb[mm][bj];
;                         rv[mm][bj][0] = (f32x4){bflo(w.x), bfhi(w.x), bflo(w.y), bfhi(w.y)}; rv[mm][bj][1] = (f32x4){bflo(w.z), bfhi(w.z), bflo(w.w), bfhi(w.w)}; }
;             }
;             __builtin_amdgcn_sched_barrier(0);
; #pragma unroll
;             for (int mm = 0; mm < 2; ++mm) {
;                 const int m = 2 * mp + mm;
;                 const int row = u.pm * BM + ai * HALF + wr * 64 + m * 16 + fr;
;                 float q = 0.f;
; #pragma unroll
;                 for (int bj = 0; bj < 2; ++bj) {
;                     const int col = u.pn * BM + bj * HALF + wc * 32 + 8 * fq;
;                     const f32x4 a = acc[ai][bj][m][0] + rv[mm][bj][0], b = acc[ai][bj][m][1] + rv[mm][bj][1];
;                     if (out) { __builtin_nontemporal_store(a, (f32x4*)(out + (size_t)row * D + col)); __builtin_nontemporal_store(b, (f32x4*)(out + (size_t)row * D + col + 4)); }
.LBB0_1420:
	s_waitcnt vmcnt(15)
	v_lshlrev_b32_e32 v50, 16, v224
	v_and_b32_e32 v51, 0xffff0000, v224
	v_lshlrev_b32_e32 v52, 16, v225
	v_and_b32_e32 v53, 0xffff0000, v225
	v_lshlrev_b32_e32 v54, 16, v226
	s_waitcnt lgkmcnt(0)
	v_and_b32_e32 v55, 0xffff0000, v226
	v_lshlrev_b32_e32 v56, 16, v227
	v_and_b32_e32 v57, 0xffff0000, v227
	v_lshlrev_b64 v[58:59], 10, v[80:81]
	v_pk_add_f32 v[48:49], v[48:49], v[52:53]
	v_pk_add_f32 v[46:47], v[46:47], v[50:51]
	v_pk_add_f32 v[44:45], v[44:45], v[56:57]
	v_pk_add_f32 v[42:43], v[42:43], v[54:55]
	s_and_b64 vcc, exec, s[8:9]
	v_lshl_add_u64 v[52:53], v[58:59], 2, s[14:15]
	s_cbranch_vccnz .LBB0_1422
	v_lshl_add_u64 v[50:51], v[156:157], 2, v[52:53]
	global_store_dwordx4 v[50:51], v[46:49], off nt
	global_store_dwordx4 v[50:51], v[42:45], off offset:16 nt

;     __device__ __forceinline__ void operator()(const f32x4 (&acc)[2][2][4][2], const Unit& u, int wr, int wc, int fr, int fq) const {
;     ...
;                     for (int bj = 0; bj < 2; ++bj) { const u32x4 w = rb[mm][bj];
;                         rv[mm][bj][0] = (f32x4){bflo(w.x), bfhi(w.x), bflo(w.y), bfhi(w.y)}; rv[mm][bj][1] = (f32x4){bflo(w.z), bfhi(w.z), bflo(w.w), bfhi(w.w)}; }
;             }
;             __builtin_amdgcn_sched_barrier(0);
; #pragma unroll
;             for (int mm = 0; mm < 2; ++mm) {
;                 const int m = 2 * mp + mm;
;                 const int row = u.pm * BM + ai * HALF + wr * 64 + m * 16 + fr;
;                 float q = 0.f;
; #pragma unroll
;                 for (int bj = 0; bj < 2; ++bj) {
;                     const int col = u.pn * BM + bj * HALF + wc * 32 + 8 * fq;
;                     const f32x4 a = acc[ai][bj][m][0] + rv[mm][bj][0], b = acc[ai][bj][m][1] + rv[mm][bj][1];
;                     if (out) { __builtin_nontemporal_store(a, (f32x4*)(out + (size_t)row * D + col)); __builtin_nontemporal_store(b, (f32x4*)(out + (size_t)row * D + col + 4)); }
.LBB0_1424:
	s_waitcnt vmcnt(15)
	v_lshlrev_b32_e32 v42, 16, v228
	v_and_b32_e32 v43, 0xffff0000, v228
	v_lshlrev_b32_e32 v44, 16, v229
	v_and_b32_e32 v45, 0xffff0000, v229
	v_lshlrev_b32_e32 v46, 16, v230
	v_and_b32_e32 v47, 0xffff0000, v230
	v_lshlrev_b32_e32 v48, 16, v231
	v_and_b32_e32 v49, 0xffff0000, v231
	v_pk_add_f32 v[40:41], v[40:41], v[44:45]
	v_pk_add_f32 v[38:39], v[38:39], v[42:43]
	v_pk_add_f32 v[36:37], v[36:37], v[48:49]
	s_and_b64 vcc, exec, s[8:9]
	v_pk_add_f32 v[34:35], v[34:35], v[46:47]
	s_cbranch_vccnz .LBB0_1426
	v_lshl_add_u64 v[42:43], v[156:157], 2, v[52:53]
	global_store_dwordx4 v[42:43], v[38:41], off offset:512 nt
	global_store_dwordx4 v[42:43], v[34:37], off offset:528 nt

;     __device__ __forceinline__ void operator()(const f32x4 (&acc)[2][2][4][2], const Unit& u, int wr, int wc, int fr, int fq) const {
;     ...
;                     for (int bj = 0; bj < 2; ++bj) { const u32x4 w = rb[mm][bj];
;                         rv[mm][bj][0] = (f32x4){bflo(w.x), bfhi(w.x), bflo(w.y), bfhi(w.y)}; rv[mm][bj][1] = (f32x4){bflo(w.z), bfhi(w.z), bflo(w.w), bfhi(w.w)}; }
;             }
;             __builtin_amdgcn_sched_barrier(0);
; #pragma unroll
;             for (int mm = 0; mm < 2; ++mm) {
;                 const int m = 2 * mp + mm;
;                 const int row = u.pm * BM + ai * HALF + wr * 64 + m * 16 + fr;
;                 float q = 0.f;
; #pragma unroll
;                 for (int bj = 0; bj < 2; ++bj) {
;                     const int col = u.pn * BM + bj * HALF + wc * 32 + 8 * fq;
;                     const f32x4 a = acc[ai][bj][m][0] + rv[mm][bj][0], b = acc[ai][bj][m][1] + rv[mm][bj][1];
;                     if (out) { __builtin_nontemporal_store(a, (f32x4*)(out + (size_t)row * D + col)); __builtin_nontemporal_store(b, (f32x4*)(out + (size_t)row * D + col + 4)); }
.LBB0_1430:
	v_add_u32_e32 v56, 0xa0, v154
	v_ashrrev_i32_e32 v57, 31, v56
	v_add_u32_e32 v48, 0xb0, v154
	v_lshlrev_b64 v[50:51], 11, v[56:57]
	v_ashrrev_i32_e32 v49, 31, v48
	v_lshl_add_u64 v[34:35], v[158:159], 0, v[50:51]
	v_lshlrev_b64 v[46:47], 11, v[48:49]
	v_lshl_add_u64 v[34:35], v[158:159], 0, v[46:47]
	s_waitcnt lgkmcnt(0)
	s_nop 0
	s_waitcnt vmcnt(15)
	v_lshlrev_b32_e32 v58, 16, v232
	v_and_b32_e32 v59, 0xffff0000, v232
	v_lshlrev_b32_e32 v52, 16, v233
	v_and_b32_e32 v53, 0xffff0000, v233
	v_lshlrev_b32_e32 v60, 16, v234
	v_and_b32_e32 v61, 0xffff0000, v234
	v_lshlrev_b32_e32 v54, 16, v235
	v_and_b32_e32 v55, 0xffff0000, v235
	v_lshlrev_b64 v[56:57], 10, v[56:57]
	v_pk_add_f32 v[32:33], v[32:33], v[52:53]
	v_pk_add_f32 v[30:31], v[30:31], v[58:59]
	v_pk_add_f32 v[28:29], v[28:29], v[54:55]
	v_pk_add_f32 v[26:27], v[26:27], v[60:61]
	s_and_b64 vcc, exec, s[8:9]
	v_lshl_add_u64 v[52:53], v[56:57], 2, s[14:15]
	s_cbranch_vccnz .LBB0_1432
	v_lshl_add_u64 v[54:55], v[156:157], 2, v[52:53]
	global_store_dwordx4 v[54:55], v[30:33], off nt
	global_store_dwordx4 v[54:55], v[26:29], off offset:16 nt

;     __device__ __forceinline__ void operator()(const f32x4 (&acc)[2][2][4][2], const Unit& u, int wr, int wc, int fr, int fq) const {
;     ...
;                     for (int bj = 0; bj < 2; ++bj) { const u32x4 w = rb[mm][bj];
;                         rv[mm][bj][0] = (f32x4){bflo(w.x), bfhi(w.x), bflo(w.y), bfhi(w.y)}; rv[mm][bj][1] = (f32x4){bflo(w.z), bfhi(w.z), bflo(w.w), bfhi(w.w)}; }
;             }
;             __builtin_amdgcn_sched_barrier(0);
; #pragma unroll
;             for (int mm = 0; mm < 2; ++mm) {
;                 const int m = 2 * mp + mm;
;                 const int row = u.pm * BM + ai * HALF + wr * 64 + m * 16 + fr;
;                 float q = 0.f;
; #pragma unroll
;                 for (int bj = 0; bj < 2; ++bj) {
;                     const int col = u.pn * BM + bj * HALF + wc * 32 + 8 * fq;
;                     const f32x4 a = acc[ai][bj][m][0] + rv[mm][bj][0], b = acc[ai][bj][m][1] + rv[mm][bj][1];
;                     if (out) { __builtin_nontemporal_store(a, (f32x4*)(out + (size_t)row * D + col)); __builtin_nontemporal_store(b, (f32x4*)(out + (size_t)row * D + col + 4)); }
.LBB0_1434:
	s_waitcnt vmcnt(15)
	v_lshlrev_b32_e32 v26, 16, v236
	v_and_b32_e32 v27, 0xffff0000, v236
	v_lshlrev_b32_e32 v28, 16, v237
	v_and_b32_e32 v29, 0xffff0000, v237
	v_lshlrev_b32_e32 v30, 16, v238
	v_and_b32_e32 v31, 0xffff0000, v238
	v_lshlrev_b32_e32 v32, 16, v239
	v_and_b32_e32 v33, 0xffff0000, v239
	v_pk_add_f32 v[24:25], v[24:25], v[28:29]
	v_pk_add_f32 v[22:23], v[22:23], v[26:27]
	v_pk_add_f32 v[20:21], v[20:21], v[32:33]
	s_and_b64 vcc, exec, s[8:9]
	v_pk_add_f32 v[18:19], v[18:19], v[30:31]
	s_cbranch_vccnz .LBB0_1436
	v_lshl_add_u64 v[26:27], v[156:157], 2, v[52:53]
	global_store_dwordx4 v[26:27], v[22:25], off offset:512 nt
	global_store_dwordx4 v[26:27], v[18:21], off offset:528 nt

;     __device__ __forceinline__ void operator()(const f32x4 (&acc)[2][2][4][2], const Unit& u, int wr, int wc, int fr, int fq) const {
;     ...
;                     for (int bj = 0; bj < 2; ++bj) { const u32x4 w = rb[mm][bj];
;                         rv[mm][bj][0] = (f32x4){bflo(w.x), bfhi(w.x), bflo(w.y), bfhi(w.y)}; rv[mm][bj][1] = (f32x4){bflo(w.z), bfhi(w.z), bflo(w.w), bfhi(w.w)}; }
;             }
;             __builtin_amdgcn_sched_barrier(0);
; #pragma unroll
;             for (int mm = 0; mm < 2; ++mm) {
;                 const int m = 2 * mp + mm;
;                 const int row = u.pm * BM + ai * HALF + wr * 64 + m * 16 + fr;
;                 float q = 0.f;
; #pragma unroll
;                 for (int bj = 0; bj < 2; ++bj) {
;                     const int col = u.pn * BM + bj * HALF + wc * 32 + 8 * fq;
;                     const f32x4 a = acc[ai][bj][m][0] + rv[mm][bj][0], b = acc[ai][bj][m][1] + rv[mm][bj][1];
;                     if (out) { __builtin_nontemporal_store(a, (f32x4*)(out + (size_t)row * D + col)); __builtin_nontemporal_store(b, (f32x4*)(out + (size_t)row * D + col + 4)); }
.LBB0_1440:
	s_waitcnt vmcnt(15)
	v_lshlrev_b32_e32 v18, 16, v240
	v_and_b32_e32 v19, 0xffff0000, v240
	v_lshlrev_b32_e32 v20, 16, v241
	v_and_b32_e32 v21, 0xffff0000, v241
	v_lshlrev_b32_e32 v22, 16, v242
	s_waitcnt lgkmcnt(0)
	v_and_b32_e32 v23, 0xffff0000, v242
	v_lshlrev_b32_e32 v24, 16, v243
	v_and_b32_e32 v25, 0xffff0000, v243
	v_lshlrev_b64 v[26:27], 10, v[48:49]
	v_pk_add_f32 v[16:17], v[16:17], v[20:21]
	v_pk_add_f32 v[14:15], v[14:15], v[18:19]
	v_pk_add_f32 v[12:13], v[12:13], v[24:25]
	v_pk_add_f32 v[10:11], v[10:11], v[22:23]
	s_and_b64 vcc, exec, s[8:9]
	v_lshl_add_u64 v[20:21], v[26:27], 2, s[14:15]
	s_cbranch_vccnz .LBB0_1442
	v_lshl_add_u64 v[18:19], v[156:157], 2, v[20:21]
	global_store_dwordx4 v[18:19], v[14:17], off nt
	global_store_dwordx4 v[18:19], v[10:13], off offset:16 nt

;     __device__ __forceinline__ void operator()(const f32x4 (&acc)[2][2][4][2], const Unit& u, int wr, int wc, int fr, int fq) const {
;     ...
;                     for (int bj = 0; bj < 2; ++bj) { const u32x4 w = rb[mm][bj];
;                         rv[mm][bj][0] = (f32x4){bflo(w.x), bfhi(w.x), bflo(w.y), bfhi(w.y)}; rv[mm][bj][1] = (f32x4){bflo(w.z), bfhi(w.z), bflo(w.w), bfhi(w.w)}; }
;             }
;             __builtin_amdgcn_sched_barrier(0);
; #pragma unroll
;             for (int mm = 0; mm < 2; ++mm) {
;                 const int m = 2 * mp + mm;
;                 const int row = u.pm * BM + ai * HALF + wr * 64 + m * 16 + fr;
;                 float q = 0.f;
; #pragma unroll
;                 for (int bj = 0; bj < 2; ++bj) {
;                     const int col = u.pn * BM + bj * HALF + wc * 32 + 8 * fq;
;                     const f32x4 a = acc[ai][bj][m][0] + rv[mm][bj][0], b = acc[ai][bj][m][1] + rv[mm][bj][1];
;                     if (out) { __builtin_nontemporal_store(a, (f32x4*)(out + (size_t)row * D + col)); __builtin_nontemporal_store(b, (f32x4*)(out + (size_t)row * D + col + 4)); }
.LBB0_1444:
	s_waitcnt vmcnt(15)
	v_lshlrev_b32_e32 v10, 16, v252
	v_and_b32_e32 v11, 0xffff0000, v252
	v_lshlrev_b32_e32 v12, 16, v253
	v_and_b32_e32 v13, 0xffff0000, v253
	v_lshlrev_b32_e32 v14, 16, v254
	v_and_b32_e32 v15, 0xffff0000, v254
	v_lshlrev_b32_e32 v16, 16, v255
	v_and_b32_e32 v17, 0xffff0000, v255
	v_pk_add_f32 v[8:9], v[8:9], v[12:13]
	v_pk_add_f32 v[6:7], v[6:7], v[10:11]
	v_pk_add_f32 v[4:5], v[4:5], v[16:17]
	s_and_b64 vcc, exec, s[8:9]
	v_pk_add_f32 v[2:3], v[2:3], v[14:15]
	s_cbranch_vccnz .LBB0_1446
	v_lshl_add_u64 v[10:11], v[156:157], 2, v[20:21]
	global_store_dwordx4 v[10:11], v[6:9], off offset:512 nt
	global_store_dwordx4 v[10:11], v[2:5], off offset:528 nt

; __global__ void __launch_bounds__(512, 2) fwd_kernel(Args a) {
	.amdhsa_kernel _Z10fwd_kernel4Args
		.amdhsa_group_segment_fixed_size 0
		.amdhsa_private_segment_fixed_size 0
		.amdhsa_kernarg_size 400
		.amdhsa_user_sgpr_count 2
		.amdhsa_user_sgpr_dispatch_ptr 0
		.amdhsa_user_sgpr_queue_ptr 0
		.amdhsa_user_sgpr_kernarg_segment_ptr 1
		.amdhsa_user_sgpr_dispatch_id 0
		.amdhsa_user_sgpr_kernarg_preload_length 0
		.amdhsa_user_sgpr_kernarg_preload_offset 0
		.amdhsa_user_sgpr_private_segment_size 0
		.amdhsa_uses_dynamic_stack 0
		.amdhsa_enable_private_segment 0
		.amdhsa_system_sgpr_workgroup_id_x 1
		.amdhsa_system_sgpr_workgroup_id_y 0
		.amdhsa_system_sgpr_workgroup_id_z 0
		.amdhsa_system_sgpr_workgroup_info 0
		.amdhsa_system_vgpr_workitem_id 2
		.amdhsa_next_free_vgpr 256
		.amdhsa_next_free_sgpr 102
		.amdhsa_accum_offset 256
		.amdhsa_reserve_vcc 1
		.amdhsa_float_round_mode_32 0
		.amdhsa_float_round_mode_16_64 0
		.amdhsa_float_denorm_mode_32 3
		.amdhsa_float_denorm_mode_16_64 3
		.amdhsa_dx10_clamp 1
		.amdhsa_ieee_mode 1
		.amdhsa_fp16_overflow 0
		.amdhsa_tg_split 0
		.amdhsa_exception_fp_ieee_invalid_op 0
		.amdhsa_exception_fp_denorm_src 0
		.amdhsa_exception_fp_ieee_div_zero 0
		.amdhsa_exception_fp_ieee_overflow 0
		.amdhsa_exception_fp_ieee_underflow 0
		.amdhsa_exception_fp_ieee_inexact 0
		.amdhsa_exception_int_div_zero 0
	.end_amdhsa_kernel

; __global__ void __launch_bounds__(512, 2) fwd_kernel(Args a) {
amdhsa.kernels:
  - .agpr_count:     0
    .args:
      - .offset:         0
        .size:           144
        .value_kind:     by_value
      - .offset:         144
        .size:           4
        .value_kind:     hidden_block_count_x
      - .offset:         148
        .size:           4
        .value_kind:     hidden_block_count_y
      - .offset:         152
        .size:           4
        .value_kind:     hidden_block_count_z
      - .offset:         156
        .size:           2
        .value_kind:     hidden_group_size_x
      - .offset:         158
        .size:           2
        .value_kind:     hidden_group_size_y
      - .offset:         160
        .size:           2
        .value_kind:     hidden_group_size_z
      - .offset:         162
        .size:           2
        .value_kind:     hidden_remainder_x
      - .offset:         164
        .size:           2
        .value_kind:     hidden_remainder_y
      - .offset:         166
        .size:           2
        .value_kind:     hidden_remainder_z
      - .offset:         184
        .size:           8
        .value_kind:     hidden_global_offset_x
      - .offset:         192
        .size:           8
        .value_kind:     hidden_global_offset_y
      - .offset:         200
        .size:           8
        .value_kind:     hidden_global_offset_z
      - .offset:         208
        .size:           2
        .value_kind:     hidden_grid_dims
      - .offset:         232
        .size:           8
        .value_kind:     hidden_multigrid_sync_arg
      - .offset:         264
        .size:           4
        .value_kind:     hidden_dynamic_lds_size
    .group_segment_fixed_size: 0
    .kernarg_segment_align: 8
    .kernarg_segment_size: 400
    .language:       OpenCL C
    .language_version:
      - 2
      - 0
    .max_flat_workgroup_size: 512
    .name:           _Z10fwd_kernel4Args
    .private_segment_fixed_size: 0
    .sgpr_count:     108
    .sgpr_spill_count: 223
    .symbol:         _Z10fwd_kernel4Args.kd
    .uniform_work_group_size: 1
    .uses_dynamic_stack: false
    .vgpr_count:     256
    .vgpr_spill_count: 0
    .wavefront_size: 64
